# in-proj and FFN-up GEMM: first K iteration of every unit peeled, first MFMA of each accumulator takes C=0, the 128 accumulator-zeroing v_mov per unit removed
# speedup vs baseline: 1.0146x; 1.0078x over previous
; #define PG8_STAGE(bufoff, gbase, voff) do { _Pragma("unroll") for (int _i = 0; _i < 2; ++_i) \
;         __builtin_amdgcn_global_load_lds((const unsigned*)((const char*)(gbase) + (voff)[_i]), (LAS unsigned*)(lds + (bufoff) + ldsw + _i * 8192), 16, 0, 0); } while (0)
; #define PG8_LDA(dst, b, h) do { _Pragma("unroll") for (int m = 0; m < 4; ++m) _Pragma("unroll") for (int k = 0; k < 2; ++k) dst[m][k] = *(const LAS bf16x8*)(lds + PG8_SA(b, h) + aoff + m * 2048 + k * 1024); } while (0)
; #define PG8_LDB(dst, b, h) do { _Pragma("unroll") for (int n = 0; n < 2; ++n) _Pragma("unroll") for (int k = 0; k < 2; ++k) dst[n][k] = *(const LAS bf16x8*)(lds + PG8_SB(b, h) + boff + n * 2048 + k * 1024); } while (0)
; #define PG8_MMA(ai, bj, At, Bt) do { __builtin_amdgcn_s_setprio(1); _Pragma("unroll") for (int m = 0; m < 4; ++m) _Pragma("unroll") for (int n = 0; n < 2; ++n) _Pragma("unroll") for (int k = 0; k < 2; ++k) \
;         acc[ai][bj][m][n] = __builtin_amdgcn_mfma_f32_16x16x32_bf16(Bt[n][k], At[m][k], acc[ai][bj][m][n], 0, 0, 0); __builtin_amdgcn_s_setprio(0); } while (0)
; #define PG8_WAIT_V(n) asm volatile("s_waitcnt vmcnt(" #n ")" ::: "memory")
; #define PG8_WAIT_L(n) asm volatile("s_waitcnt lgkmcnt(" #n ")" ::: "memory")
; #define PG8_BAR __builtin_amdgcn_s_barrier()
; #define PG8_SCHED __builtin_amdgcn_sched_barrier(0)
; template <class Epi>
; __device__ __forceinline__ void gemm_phase(LAS unsigned char* lds, const Gemm g, const int G, const int cidx, const Epi& E) {
;     ...
;         const bool has_next = S.next(ui + 1, nxt);
;         const char* nA = has_next ? PG8_ABASE(nxt) : cA; const char* nB = has_next ? (const char*)g.Bt + (size_t)nxt.pn * tstep : cB;
;         for (int t = 0; t < nt; t += 2) {
;             const bool last = (t == nt - 2);
;             const char* a1 = cA + (size_t)(t + 1) * kstep;
;             const char* a2 = last ? nA : cA + (size_t)(t + 2) * kstep; const char* b2 = last ? nB : cB + (size_t)(t + 2) * kstep;
;             const char* a3 = a2 + kstep; const char* b3 = b2 + kstep;
;             PG8_LDB(B0, 0, 0); PG8_LDB(B1, 0, 1); PG8_SCHED; PG8_LDA(At, 0, 0); PG8_STAGE(PG8_SA(1, 1), a1 + hstep, voffA);
;             PG8_WAIT_V(8); PG8_WAIT_L(0); PG8_BAR; PG8_MMA(0, 0, At, B0); PG8_MMA(0, 1, At, B1); PG8_BAR; PG8_SCHED;
.LBB0_81:
	s_ashr_i32 s13, s12, 31
	v_cmp_lt_i64_e32 vcc, s[14:15], v[240:241]
	s_lshl_b64 s[14:15], s[12:13], 19
	s_add_u32 s14, s42, s14
	s_addc_u32 s15, s94, s15
	s_and_b64 s[18:19], vcc, exec
	s_cselect_b32 s13, s15, s27
	s_cselect_b32 s17, s14, s26
	s_ashr_i32 s9, s8, 31
	s_lshl_b64 s[18:19], s[8:9], 19
	s_add_u32 s18, s96, s18
	s_addc_u32 s19, s97, s19
	s_and_b64 s[28:29], vcc, exec
	s_cselect_b32 s9, s19, s25
	s_cselect_b32 s22, s18, s24
	s_add_u32 s33, s24, 0x100
	s_addc_u32 s44, s25, 0
	s_add_u32 s24, s26, 0x40080
	s_addc_u32 s25, s27, 0
	s_mov_b32 s45, -2
	s_add_u32 s26, s24, 0xfffc0080
	s_addc_u32 s27, s25, -1
	s_add_i32 s43, 0, 0x10000
	s_cmp_eq_u32 s45, 12
	s_cselect_b32 s29, s13, s27
	s_cselect_b32 s28, s17, s26
	s_cselect_b32 s27, s9, s44
	s_cselect_b32 s26, s22, s33
	s_add_i32 s68, 0, 0x14000
	v_add_u32_e32 v162, s43, v145
	v_add_u32_e32 v178, s68, v145
	ds_read_b128 v[132:135], v162
	ds_read_b128 v[140:143], v162 offset:1024
	ds_read_b128 v[156:159], v162 offset:2048
	ds_read_b128 v[162:165], v162 offset:3072
	ds_read_b128 v[166:169], v178
	ds_read_b128 v[170:173], v178 offset:1024
	ds_read_b128 v[174:177], v178 offset:2048
	ds_read_b128 v[178:181], v178 offset:3072
	v_lshl_add_u64 v[226:227], s[24:25], 0, v[154:155]
	s_add_i32 m0, s21, 0xc000
	ds_read_b128 v[182:185], v161
	ds_read_b128 v[186:189], v161 offset:1024
	ds_read_b128 v[190:193], v161 offset:2048
	ds_read_b128 v[194:197], v161 offset:3072
	ds_read_b128 v[198:201], v161 offset:4096
	ds_read_b128 v[214:217], v161 offset:5120
	ds_read_b128 v[218:221], v161 offset:6144
	ds_read_b128 v[222:225], v161 offset:7168
	global_load_lds_dwordx4 v[226:227], off
	v_lshl_add_u64 v[226:227], s[24:25], 0, v[152:153]
	s_add_i32 m0, s21, 0xe000
	s_nop 0
	global_load_lds_dwordx4 v[226:227], off
	s_waitcnt vmcnt(8)
	s_waitcnt lgkmcnt(0)
	s_barrier
	s_setprio 1
	s_waitcnt lgkmcnt(0)
	v_mfma_f32_16x16x32_bf16 v[128:131], v[132:135], v[182:185], 0
	v_mfma_f32_16x16x32_bf16 v[120:123], v[156:159], v[182:185], 0
	v_mfma_f32_16x16x32_bf16 v[112:115], v[132:135], v[190:193], 0
	v_mfma_f32_16x16x32_bf16 v[104:107], v[156:159], v[190:193], 0
	v_mfma_f32_16x16x32_bf16 v[96:99], v[132:135], v[198:201], 0
	v_mfma_f32_16x16x32_bf16 v[88:91], v[156:159], v[198:201], 0
	v_mfma_f32_16x16x32_bf16 v[80:83], v[132:135], v[218:221], 0
	v_mfma_f32_16x16x32_bf16 v[72:75], v[156:159], v[218:221], 0
	v_mfma_f32_16x16x32_bf16 v[128:131], v[140:143], v[186:189], v[128:131]
	v_mfma_f32_16x16x32_bf16 v[120:123], v[162:165], v[186:189], v[120:123]
	v_mfma_f32_16x16x32_bf16 v[112:115], v[140:143], v[194:197], v[112:115]
	v_mfma_f32_16x16x32_bf16 v[104:107], v[162:165], v[194:197], v[104:107]
	v_mfma_f32_16x16x32_bf16 v[96:99], v[140:143], v[214:217], v[96:99]
	v_mfma_f32_16x16x32_bf16 v[88:91], v[162:165], v[214:217], v[88:91]
	v_mfma_f32_16x16x32_bf16 v[80:83], v[140:143], v[222:225], v[80:83]
	v_mfma_f32_16x16x32_bf16 v[72:75], v[162:165], v[222:225], v[72:75]
	s_setprio 0
	s_setprio 1
	v_mfma_f32_16x16x32_bf16 v[124:127], v[166:169], v[182:185], 0
	v_mfma_f32_16x16x32_bf16 v[116:119], v[174:177], v[182:185], 0
	v_mfma_f32_16x16x32_bf16 v[108:111], v[166:169], v[190:193], 0
	v_mfma_f32_16x16x32_bf16 v[100:103], v[174:177], v[190:193], 0
	v_mfma_f32_16x16x32_bf16 v[92:95], v[166:169], v[198:201], 0
	v_mfma_f32_16x16x32_bf16 v[84:87], v[174:177], v[198:201], 0
	v_mfma_f32_16x16x32_bf16 v[76:79], v[166:169], v[218:221], 0
	v_mfma_f32_16x16x32_bf16 v[68:71], v[174:177], v[218:221], 0
	v_mfma_f32_16x16x32_bf16 v[124:127], v[170:173], v[186:189], v[124:127]
	v_mfma_f32_16x16x32_bf16 v[116:119], v[178:181], v[186:189], v[116:119]
	v_mfma_f32_16x16x32_bf16 v[108:111], v[170:173], v[194:197], v[108:111]
	v_mfma_f32_16x16x32_bf16 v[100:103], v[178:181], v[194:197], v[100:103]
	v_mfma_f32_16x16x32_bf16 v[92:95], v[170:173], v[214:217], v[92:95]
	v_mfma_f32_16x16x32_bf16 v[84:87], v[178:181], v[214:217], v[84:87]
	v_mfma_f32_16x16x32_bf16 v[76:79], v[170:173], v[222:225], v[76:79]
	v_mfma_f32_16x16x32_bf16 v[68:71], v[178:181], v[222:225], v[68:71]
	s_setprio 0
	s_barrier
	s_add_i32 s43, s43, s36
	v_lshl_add_u64 v[226:227], s[26:27], 0, v[148:149]
	s_mov_b32 m0, s43
	ds_read_b128 v[182:185], v161 offset:16384
	ds_read_b128 v[186:189], v161 offset:17408
	ds_read_b128 v[190:193], v161 offset:18432
	ds_read_b128 v[194:197], v161 offset:19456
	ds_read_b128 v[198:201], v161 offset:20480
	ds_read_b128 v[214:217], v161 offset:21504
	ds_read_b128 v[218:221], v161 offset:22528
	ds_read_b128 v[222:225], v161 offset:23552
	global_load_lds_dwordx4 v[226:227], off
	s_add_i32 m0, s43, 0x2000
	s_add_u32 s76, s26, 0x40000
	v_lshl_add_u64 v[228:229], s[26:27], 0, v[0:1]
	s_addc_u32 s77, s27, 0
	s_add_i32 s43, s68, s36
	global_load_lds_dwordx4 v[228:229], off
	v_lshl_add_u64 v[230:231], s[76:77], 0, v[148:149]
	s_mov_b32 m0, s43
	v_lshl_add_u64 v[232:233], s[28:29], 0, v[146:147]
	global_load_lds_dwordx4 v[230:231], off
	v_lshl_add_u64 v[230:231], s[76:77], 0, v[0:1]
	s_add_i32 m0, s43, 0x2000
	s_nop 0
	global_load_lds_dwordx4 v[230:231], off
	v_lshl_add_u64 v[230:231], s[28:29], 0, v[150:151]
	s_mov_b32 m0, s21
	s_nop 0
	global_load_lds_dwordx4 v[230:231], off
	s_mov_b32 m0, s38
	s_nop 0
	global_load_lds_dwordx4 v[232:233], off
	s_waitcnt vmcnt(8)
	s_waitcnt lgkmcnt(0)
	s_barrier
; #define PG8_STAGE(bufoff, gbase, voff) do { _Pragma("unroll") for (int _i = 0; _i < 2; ++_i) \
;         __builtin_amdgcn_global_load_lds((const unsigned*)((const char*)(gbase) + (voff)[_i]), (LAS unsigned*)(lds + (bufoff) + ldsw + _i * 8192), 16, 0, 0); } while (0)
; #define PG8_LDA(dst, b, h) do { _Pragma("unroll") for (int m = 0; m < 4; ++m) _Pragma("unroll") for (int k = 0; k < 2; ++k) dst[m][k] = *(const LAS bf16x8*)(lds + PG8_SA(b, h) + aoff + m * 2048 + k * 1024); } while (0)
; #define PG8_LDB(dst, b, h) do { _Pragma("unroll") for (int n = 0; n < 2; ++n) _Pragma("unroll") for (int k = 0; k < 2; ++k) dst[n][k] = *(const LAS bf16x8*)(lds + PG8_SB(b, h) + boff + n * 2048 + k * 1024); } while (0)
; #define PG8_MMA(ai, bj, At, Bt) do { __builtin_amdgcn_s_setprio(1); _Pragma("unroll") for (int m = 0; m < 4; ++m) _Pragma("unroll") for (int n = 0; n < 2; ++n) _Pragma("unroll") for (int k = 0; k < 2; ++k) \
;         acc[ai][bj][m][n] = __builtin_amdgcn_mfma_f32_16x16x32_bf16(Bt[n][k], At[m][k], acc[ai][bj][m][n], 0, 0, 0); __builtin_amdgcn_s_setprio(0); } while (0)
; #define PG8_WAIT_V(n) asm volatile("s_waitcnt vmcnt(" #n ")" ::: "memory")
; #define PG8_WAIT_L(n) asm volatile("s_waitcnt lgkmcnt(" #n ")" ::: "memory")
; #define PG8_BAR __builtin_amdgcn_s_barrier()
; #define PG8_SCHED __builtin_amdgcn_sched_barrier(0)
; template <class Epi>
; __device__ __forceinline__ void gemm_phase(LAS unsigned char* lds, const Gemm g, const int G, const int cidx, const Epi& E) {
;     ...
;             PG8_LDA(At, 0, 1); PG8_STAGE(PG8_SB(0, 0), b2, voffB); PG8_STAGE(PG8_SB(0, 1), b2 + hstep, voffB); PG8_STAGE(PG8_SA(0, 0), a2, voffA);
;             PG8_WAIT_V(8); PG8_WAIT_L(0); PG8_BAR; PG8_MMA(1, 0, At, B0); PG8_MMA(1, 1, At, B1); PG8_BAR; PG8_SCHED;
;             PG8_LDB(B0, 1, 0); PG8_LDB(B1, 1, 1); PG8_SCHED; PG8_LDA(At, 1, 0); PG8_STAGE(PG8_SA(0, 1), a2 + hstep, voffA);
;             PG8_WAIT_V(8); PG8_WAIT_L(0); PG8_BAR; PG8_MMA(0, 0, At, B0); PG8_MMA(0, 1, At, B1); PG8_BAR; PG8_SCHED;
	s_setprio 1
	s_waitcnt lgkmcnt(0)
	v_mfma_f32_16x16x32_bf16 v[64:67], v[132:135], v[182:185], 0
	v_mfma_f32_16x16x32_bf16 v[56:59], v[156:159], v[182:185], 0
	v_mfma_f32_16x16x32_bf16 v[48:51], v[132:135], v[190:193], 0
	v_mfma_f32_16x16x32_bf16 v[40:43], v[156:159], v[190:193], 0
	v_mfma_f32_16x16x32_bf16 v[32:35], v[132:135], v[198:201], 0
	v_mfma_f32_16x16x32_bf16 v[24:27], v[156:159], v[198:201], 0
	v_mfma_f32_16x16x32_bf16 v[16:19], v[132:135], v[218:221], 0
	v_mfma_f32_16x16x32_bf16 v[8:11], v[156:159], v[218:221], 0
	v_mfma_f32_16x16x32_bf16 v[64:67], v[140:143], v[186:189], v[64:67]
	v_mfma_f32_16x16x32_bf16 v[56:59], v[162:165], v[186:189], v[56:59]
	v_mfma_f32_16x16x32_bf16 v[48:51], v[140:143], v[194:197], v[48:51]
	v_mfma_f32_16x16x32_bf16 v[40:43], v[162:165], v[194:197], v[40:43]
	v_mfma_f32_16x16x32_bf16 v[32:35], v[140:143], v[214:217], v[32:35]
	v_mfma_f32_16x16x32_bf16 v[24:27], v[162:165], v[214:217], v[24:27]
	v_mfma_f32_16x16x32_bf16 v[16:19], v[140:143], v[222:225], v[16:19]
	v_mfma_f32_16x16x32_bf16 v[8:11], v[162:165], v[222:225], v[8:11]
	s_setprio 0
	s_setprio 1
	v_mfma_f32_16x16x32_bf16 v[60:63], v[166:169], v[182:185], 0
	v_mfma_f32_16x16x32_bf16 v[52:55], v[174:177], v[182:185], 0
	v_mfma_f32_16x16x32_bf16 v[44:47], v[166:169], v[190:193], 0
	v_mfma_f32_16x16x32_bf16 v[36:39], v[174:177], v[190:193], 0
	v_mfma_f32_16x16x32_bf16 v[28:31], v[166:169], v[198:201], 0
	v_mfma_f32_16x16x32_bf16 v[20:23], v[174:177], v[198:201], 0
	v_mfma_f32_16x16x32_bf16 v[12:15], v[166:169], v[218:221], 0
	v_mfma_f32_16x16x32_bf16 v[4:7], v[174:177], v[218:221], 0
	v_mfma_f32_16x16x32_bf16 v[60:63], v[170:173], v[186:189], v[60:63]
	v_mfma_f32_16x16x32_bf16 v[52:55], v[178:181], v[186:189], v[52:55]
	v_mfma_f32_16x16x32_bf16 v[44:47], v[170:173], v[194:197], v[44:47]
	v_mfma_f32_16x16x32_bf16 v[36:39], v[178:181], v[194:197], v[36:39]
	v_mfma_f32_16x16x32_bf16 v[28:31], v[170:173], v[214:217], v[28:31]
	v_mfma_f32_16x16x32_bf16 v[20:23], v[178:181], v[214:217], v[20:23]
	v_mfma_f32_16x16x32_bf16 v[12:15], v[170:173], v[222:225], v[12:15]
	v_mfma_f32_16x16x32_bf16 v[4:7], v[178:181], v[222:225], v[4:7]
	s_setprio 0
	s_barrier
	s_add_i32 s43, 0, 0x18000
	s_add_i32 s68, 0, 0x1c000
	v_add_u32_e32 v162, s43, v145
	v_add_u32_e32 v178, s68, v145
	ds_read_b128 v[132:135], v162
	ds_read_b128 v[140:143], v162 offset:1024
	ds_read_b128 v[156:159], v162 offset:2048
	ds_read_b128 v[162:165], v162 offset:3072
	ds_read_b128 v[166:169], v178
	ds_read_b128 v[170:173], v178 offset:1024
	ds_read_b128 v[174:177], v178 offset:2048
	ds_read_b128 v[178:181], v178 offset:3072
	s_add_u32 s28, s28, 0x40000
	s_addc_u32 s29, s29, 0
	s_mov_b32 m0, s39
	v_lshl_add_u64 v[234:235], s[28:29], 0, v[150:151]
	ds_read_b128 v[182:185], v161 offset:32768
	ds_read_b128 v[186:189], v161 offset:33792
	ds_read_b128 v[190:193], v161 offset:34816
	ds_read_b128 v[194:197], v161 offset:35840
	ds_read_b128 v[198:201], v161 offset:36864
	ds_read_b128 v[214:217], v161 offset:37888
	ds_read_b128 v[218:221], v161 offset:38912
	ds_read_b128 v[222:225], v161 offset:39936
	global_load_lds_dwordx4 v[234:235], off
	v_lshl_add_u64 v[234:235], s[28:29], 0, v[146:147]
	s_mov_b32 m0, s75
	s_nop 0
	global_load_lds_dwordx4 v[234:235], off
	s_waitcnt vmcnt(8)
	s_waitcnt lgkmcnt(0)
	s_barrier
	s_setprio 1
	s_waitcnt lgkmcnt(0)
	v_mfma_f32_16x16x32_bf16 v[128:131], v[132:135], v[182:185], v[128:131]
	v_mfma_f32_16x16x32_bf16 v[120:123], v[156:159], v[182:185], v[120:123]
	v_mfma_f32_16x16x32_bf16 v[112:115], v[132:135], v[190:193], v[112:115]
	v_mfma_f32_16x16x32_bf16 v[104:107], v[156:159], v[190:193], v[104:107]
	v_mfma_f32_16x16x32_bf16 v[96:99], v[132:135], v[198:201], v[96:99]
	v_mfma_f32_16x16x32_bf16 v[88:91], v[156:159], v[198:201], v[88:91]
	v_mfma_f32_16x16x32_bf16 v[80:83], v[132:135], v[218:221], v[80:83]
	v_mfma_f32_16x16x32_bf16 v[72:75], v[156:159], v[218:221], v[72:75]
	v_mfma_f32_16x16x32_bf16 v[128:131], v[140:143], v[186:189], v[128:131]
	v_mfma_f32_16x16x32_bf16 v[120:123], v[162:165], v[186:189], v[120:123]
	v_mfma_f32_16x16x32_bf16 v[112:115], v[140:143], v[194:197], v[112:115]
	v_mfma_f32_16x16x32_bf16 v[104:107], v[162:165], v[194:197], v[104:107]
	v_mfma_f32_16x16x32_bf16 v[96:99], v[140:143], v[214:217], v[96:99]
	v_mfma_f32_16x16x32_bf16 v[88:91], v[162:165], v[214:217], v[88:91]
	v_mfma_f32_16x16x32_bf16 v[80:83], v[140:143], v[222:225], v[80:83]
	v_mfma_f32_16x16x32_bf16 v[72:75], v[162:165], v[222:225], v[72:75]
	s_setprio 0
	s_setprio 1
	v_mfma_f32_16x16x32_bf16 v[124:127], v[166:169], v[182:185], v[124:127]
	v_mfma_f32_16x16x32_bf16 v[116:119], v[174:177], v[182:185], v[116:119]
	v_mfma_f32_16x16x32_bf16 v[108:111], v[166:169], v[190:193], v[108:111]
	v_mfma_f32_16x16x32_bf16 v[100:103], v[174:177], v[190:193], v[100:103]
	v_mfma_f32_16x16x32_bf16 v[92:95], v[166:169], v[198:201], v[92:95]
	v_mfma_f32_16x16x32_bf16 v[84:87], v[174:177], v[198:201], v[84:87]
	v_mfma_f32_16x16x32_bf16 v[76:79], v[166:169], v[218:221], v[76:79]
	v_mfma_f32_16x16x32_bf16 v[68:71], v[174:177], v[218:221], v[68:71]
	v_mfma_f32_16x16x32_bf16 v[124:127], v[170:173], v[186:189], v[124:127]
	v_mfma_f32_16x16x32_bf16 v[116:119], v[178:181], v[186:189], v[116:119]
	v_mfma_f32_16x16x32_bf16 v[108:111], v[170:173], v[194:197], v[108:111]
	v_mfma_f32_16x16x32_bf16 v[100:103], v[178:181], v[194:197], v[100:103]
	v_mfma_f32_16x16x32_bf16 v[92:95], v[170:173], v[214:217], v[92:95]
	v_mfma_f32_16x16x32_bf16 v[84:87], v[178:181], v[214:217], v[84:87]
	v_mfma_f32_16x16x32_bf16 v[76:79], v[170:173], v[222:225], v[76:79]
	v_mfma_f32_16x16x32_bf16 v[68:71], v[178:181], v[222:225], v[68:71]
	s_setprio 0
	s_barrier
; #define PG8_STAGE(bufoff, gbase, voff) do { _Pragma("unroll") for (int _i = 0; _i < 2; ++_i) \
;         __builtin_amdgcn_global_load_lds((const unsigned*)((const char*)(gbase) + (voff)[_i]), (LAS unsigned*)(lds + (bufoff) + ldsw + _i * 8192), 16, 0, 0); } while (0)
; #define PG8_LDA(dst, b, h) do { _Pragma("unroll") for (int m = 0; m < 4; ++m) _Pragma("unroll") for (int k = 0; k < 2; ++k) dst[m][k] = *(const LAS bf16x8*)(lds + PG8_SA(b, h) + aoff + m * 2048 + k * 1024); } while (0)
; #define PG8_MMA(ai, bj, At, Bt) do { __builtin_amdgcn_s_setprio(1); _Pragma("unroll") for (int m = 0; m < 4; ++m) _Pragma("unroll") for (int n = 0; n < 2; ++n) _Pragma("unroll") for (int k = 0; k < 2; ++k) \
;         acc[ai][bj][m][n] = __builtin_amdgcn_mfma_f32_16x16x32_bf16(Bt[n][k], At[m][k], acc[ai][bj][m][n], 0, 0, 0); __builtin_amdgcn_s_setprio(0); } while (0)
; #define PG8_WAIT_V(n) asm volatile("s_waitcnt vmcnt(" #n ")" ::: "memory")
; #define PG8_WAIT_L(n) asm volatile("s_waitcnt lgkmcnt(" #n ")" ::: "memory")
; #define PG8_BAR __builtin_amdgcn_s_barrier()
; #define PG8_SCHED __builtin_amdgcn_sched_barrier(0)
; template <class Epi>
; __device__ __forceinline__ void gemm_phase(LAS unsigned char* lds, const Gemm g, const int G, const int cidx, const Epi& E) {
;     ...
;             PG8_LDA(At, 1, 1); PG8_STAGE(PG8_SB(1, 0), b3, voffB); PG8_STAGE(PG8_SB(1, 1), b3 + hstep, voffB); PG8_STAGE(PG8_SA(1, 0), a3, voffA);
;             PG8_WAIT_V(8); PG8_WAIT_L(0); PG8_BAR; PG8_MMA(1, 0, At, B0); PG8_MMA(1, 1, At, B1); PG8_BAR; PG8_SCHED;
	s_add_i32 s28, s43, s36
	v_lshl_add_u64 v[226:227], v[226:227], 0, s[46:47]
	s_mov_b32 m0, s28
	ds_read_b128 v[182:185], v161 offset:49152
	ds_read_b128 v[186:189], v161 offset:50176
	ds_read_b128 v[190:193], v161 offset:51200
	ds_read_b128 v[194:197], v161 offset:52224
	ds_read_b128 v[198:201], v161 offset:53248
	ds_read_b128 v[214:217], v161 offset:54272
	ds_read_b128 v[218:221], v161 offset:55296
	ds_read_b128 v[222:225], v161 offset:56320
	global_load_lds_dwordx4 v[226:227], off
	s_add_i32 m0, s28, 0x2000
	s_add_u32 s26, s26, 0x40080
	v_lshl_add_u64 v[226:227], v[228:229], 0, s[46:47]
	s_addc_u32 s27, s27, 0
	s_add_i32 s28, s68, s36
	global_load_lds_dwordx4 v[226:227], off
	v_lshl_add_u64 v[226:227], s[26:27], 0, v[148:149]
	s_mov_b32 m0, s28
	s_nop 0
	global_load_lds_dwordx4 v[226:227], off
	v_lshl_add_u64 v[226:227], s[26:27], 0, v[0:1]
	s_add_i32 m0, s28, 0x2000
	s_nop 0
	global_load_lds_dwordx4 v[226:227], off
	v_lshl_add_u64 v[226:227], v[230:231], 0, s[46:47]
	s_mov_b32 m0, s79
	s_nop 0
	global_load_lds_dwordx4 v[226:227], off
	v_lshl_add_u64 v[226:227], v[232:233], 0, s[46:47]
	s_mov_b32 m0, s34
	s_nop 0
	global_load_lds_dwordx4 v[226:227], off
	s_waitcnt vmcnt(8)
	s_waitcnt lgkmcnt(0)
	s_barrier
	s_setprio 1
	s_waitcnt lgkmcnt(0)
	v_mfma_f32_16x16x32_bf16 v[64:67], v[132:135], v[182:185], v[64:67]
	v_mfma_f32_16x16x32_bf16 v[56:59], v[156:159], v[182:185], v[56:59]
	v_mfma_f32_16x16x32_bf16 v[48:51], v[132:135], v[190:193], v[48:51]
	v_mfma_f32_16x16x32_bf16 v[40:43], v[156:159], v[190:193], v[40:43]
	v_mfma_f32_16x16x32_bf16 v[32:35], v[132:135], v[198:201], v[32:35]
	v_mfma_f32_16x16x32_bf16 v[24:27], v[156:159], v[198:201], v[24:27]
	v_mfma_f32_16x16x32_bf16 v[16:19], v[132:135], v[218:221], v[16:19]
	v_mfma_f32_16x16x32_bf16 v[8:11], v[156:159], v[218:221], v[8:11]
	v_mfma_f32_16x16x32_bf16 v[64:67], v[140:143], v[186:189], v[64:67]
	v_mfma_f32_16x16x32_bf16 v[56:59], v[162:165], v[186:189], v[56:59]
	v_mfma_f32_16x16x32_bf16 v[48:51], v[140:143], v[194:197], v[48:51]
	v_mfma_f32_16x16x32_bf16 v[40:43], v[162:165], v[194:197], v[40:43]
	v_mfma_f32_16x16x32_bf16 v[32:35], v[140:143], v[214:217], v[32:35]
	v_mfma_f32_16x16x32_bf16 v[24:27], v[162:165], v[214:217], v[24:27]
	v_mfma_f32_16x16x32_bf16 v[16:19], v[140:143], v[222:225], v[16:19]
	v_mfma_f32_16x16x32_bf16 v[8:11], v[162:165], v[222:225], v[8:11]
	s_setprio 0
	s_setprio 1
	v_mfma_f32_16x16x32_bf16 v[60:63], v[166:169], v[182:185], v[60:63]
	v_mfma_f32_16x16x32_bf16 v[52:55], v[174:177], v[182:185], v[52:55]
	v_mfma_f32_16x16x32_bf16 v[44:47], v[166:169], v[190:193], v[44:47]
	v_mfma_f32_16x16x32_bf16 v[36:39], v[174:177], v[190:193], v[36:39]
	v_mfma_f32_16x16x32_bf16 v[28:31], v[166:169], v[198:201], v[28:31]
	v_mfma_f32_16x16x32_bf16 v[20:23], v[174:177], v[198:201], v[20:23]
	v_mfma_f32_16x16x32_bf16 v[12:15], v[166:169], v[218:221], v[12:15]
	v_mfma_f32_16x16x32_bf16 v[4:7], v[174:177], v[218:221], v[4:7]
	v_mfma_f32_16x16x32_bf16 v[60:63], v[170:173], v[186:189], v[60:63]
	v_mfma_f32_16x16x32_bf16 v[52:55], v[178:181], v[186:189], v[52:55]
	v_mfma_f32_16x16x32_bf16 v[44:47], v[170:173], v[194:197], v[44:47]
	v_mfma_f32_16x16x32_bf16 v[36:39], v[178:181], v[194:197], v[36:39]
	v_mfma_f32_16x16x32_bf16 v[28:31], v[170:173], v[214:217], v[28:31]
	v_mfma_f32_16x16x32_bf16 v[20:23], v[178:181], v[214:217], v[20:23]
	v_mfma_f32_16x16x32_bf16 v[12:15], v[170:173], v[222:225], v[12:15]
	v_mfma_f32_16x16x32_bf16 v[4:7], v[178:181], v[222:225], v[4:7]
	s_setprio 0
	s_barrier
	s_add_i32 s45, s45, 2
	s_add_u32 s33, s33, 0x100
	s_addc_u32 s44, s44, 0
	s_add_u32 s24, s24, 0x100
	s_addc_u32 s25, s25, 0

; #define PG8_STAGE(bufoff, gbase, voff) do { _Pragma("unroll") for (int _i = 0; _i < 2; ++_i) \
;         __builtin_amdgcn_global_load_lds((const unsigned*)((const char*)(gbase) + (voff)[_i]), (LAS unsigned*)(lds + (bufoff) + ldsw + _i * 8192), 16, 0, 0); } while (0)
; #define PG8_LDA(dst, b, h) do { _Pragma("unroll") for (int m = 0; m < 4; ++m) _Pragma("unroll") for (int k = 0; k < 2; ++k) dst[m][k] = *(const LAS bf16x8*)(lds + PG8_SA(b, h) + aoff + m * 2048 + k * 1024); } while (0)
; #define PG8_LDB(dst, b, h) do { _Pragma("unroll") for (int n = 0; n < 2; ++n) _Pragma("unroll") for (int k = 0; k < 2; ++k) dst[n][k] = *(const LAS bf16x8*)(lds + PG8_SB(b, h) + boff + n * 2048 + k * 1024); } while (0)
; #define PG8_MMA(ai, bj, At, Bt) do { __builtin_amdgcn_s_setprio(1); _Pragma("unroll") for (int m = 0; m < 4; ++m) _Pragma("unroll") for (int n = 0; n < 2; ++n) _Pragma("unroll") for (int k = 0; k < 2; ++k) \
;         acc[ai][bj][m][n] = __builtin_amdgcn_mfma_f32_16x16x32_bf16(Bt[n][k], At[m][k], acc[ai][bj][m][n], 0, 0, 0); __builtin_amdgcn_s_setprio(0); } while (0)
; #define PG8_WAIT_V(n) asm volatile("s_waitcnt vmcnt(" #n ")" ::: "memory")
; #define PG8_WAIT_L(n) asm volatile("s_waitcnt lgkmcnt(" #n ")" ::: "memory")
; #define PG8_BAR __builtin_amdgcn_s_barrier()
; #define PG8_SCHED __builtin_amdgcn_sched_barrier(0)
; template <class Epi>
; __device__ __forceinline__ void gemm_phase(LAS unsigned char* lds, const Gemm g, const int G, const int cidx, const Epi& E) {
;     ...
;         const bool has_next = S.next(ui + 1, nxt);
;         const char* nA = has_next ? PG8_ABASE(nxt) : cA; const char* nB = has_next ? (const char*)g.Bt + (size_t)nxt.pn * tstep : cB;
;         for (int t = 0; t < nt; t += 2) {
;             const bool last = (t == nt - 2);
;             const char* a1 = cA + (size_t)(t + 1) * kstep;
;             const char* a2 = last ? nA : cA + (size_t)(t + 2) * kstep; const char* b2 = last ? nB : cB + (size_t)(t + 2) * kstep;
;             const char* a3 = a2 + kstep; const char* b3 = b2 + kstep;
;             PG8_LDB(B0, 0, 0); PG8_LDB(B1, 0, 1); PG8_SCHED; PG8_LDA(At, 0, 0); PG8_STAGE(PG8_SA(1, 1), a1 + hstep, voffA);
;             PG8_WAIT_V(8); PG8_WAIT_L(0); PG8_BAR; PG8_MMA(0, 0, At, B0); PG8_MMA(0, 1, At, B1); PG8_BAR; PG8_SCHED;
.LBB0_600:
	s_ashr_i32 s11, s10, 31
	v_cmp_lt_i64_e32 vcc, s[12:13], v[244:245]
	s_lshl_b64 s[12:13], s[10:11], 19
	s_add_u32 s12, s74, s12
	s_addc_u32 s13, s75, s13
	s_and_b64 s[14:15], vcc, exec
	s_cselect_b32 s11, s13, s25
	s_cselect_b32 s19, s12, s24
	s_ashr_i32 s9, s8, 31
	s_lshl_b64 s[14:15], s[8:9], 19
	s_add_u32 s14, s88, s14
	s_addc_u32 s15, s94, s15
	s_and_b64 s[26:27], vcc, exec
	s_cselect_b32 s9, s15, s21
	s_cselect_b32 s33, s14, s20
	s_add_u32 s42, s20, 0x100
	s_addc_u32 s44, s21, 0
	s_add_u32 s20, s24, 0x40080
	s_addc_u32 s21, s25, 0
	s_mov_b32 s45, -2
	s_add_u32 s24, s20, 0xfffc0080
	s_addc_u32 s25, s21, -1
	s_add_i32 s43, 0, 0x10000
	s_cmp_eq_u32 s45, 12
	s_cselect_b32 s27, s11, s25
	s_cselect_b32 s26, s19, s24
	v_add_u32_e32 v132, s43, v145
	s_cselect_b32 s25, s9, s44
	s_cselect_b32 s24, s33, s42
	s_add_i32 s68, 0, 0x14000
	ds_read_b128 v[158:161], v132
	ds_read_b128 v[164:167], v132 offset:1024
	ds_read_b128 v[168:171], v132 offset:2048
	ds_read_b128 v[172:175], v132 offset:3072
	v_add_u32_e32 v132, s68, v145
	ds_read_b128 v[176:179], v132
	ds_read_b128 v[180:183], v132 offset:1024
	ds_read_b128 v[184:187], v132 offset:2048
	ds_read_b128 v[188:191], v132 offset:3072
	v_lshl_add_u64 v[132:133], s[20:21], 0, v[156:157]
	s_add_i32 m0, s97, 0xc000
	ds_read_b128 v[192:195], v163
	ds_read_b128 v[196:199], v163 offset:1024
	ds_read_b128 v[214:217], v163 offset:2048
	ds_read_b128 v[218:221], v163 offset:3072
	ds_read_b128 v[222:225], v163 offset:4096
	ds_read_b128 v[226:229], v163 offset:5120
	ds_read_b128 v[230:233], v163 offset:6144
	ds_read_b128 v[234:237], v163 offset:7168
	global_load_lds_dwordx4 v[132:133], off
	v_lshl_add_u64 v[132:133], s[20:21], 0, v[154:155]
	s_add_i32 m0, s97, 0xe000
	s_nop 0
	global_load_lds_dwordx4 v[132:133], off
	s_waitcnt vmcnt(8)
	s_waitcnt lgkmcnt(0)
	s_barrier
	s_setprio 1
	s_waitcnt lgkmcnt(0)
	v_mfma_f32_16x16x32_bf16 v[128:131], v[158:161], v[192:195], 0
	v_mfma_f32_16x16x32_bf16 v[124:127], v[168:171], v[192:195], 0
	v_mfma_f32_16x16x32_bf16 v[120:123], v[158:161], v[214:217], 0
	v_mfma_f32_16x16x32_bf16 v[112:115], v[168:171], v[214:217], 0
	v_mfma_f32_16x16x32_bf16 v[104:107], v[158:161], v[222:225], 0
	v_mfma_f32_16x16x32_bf16 v[96:99], v[168:171], v[222:225], 0
	v_mfma_f32_16x16x32_bf16 v[88:91], v[158:161], v[230:233], 0
	v_mfma_f32_16x16x32_bf16 v[80:83], v[168:171], v[230:233], 0
	v_mfma_f32_16x16x32_bf16 v[128:131], v[164:167], v[196:199], v[128:131]
	v_mfma_f32_16x16x32_bf16 v[124:127], v[172:175], v[196:199], v[124:127]
	v_mfma_f32_16x16x32_bf16 v[120:123], v[164:167], v[218:221], v[120:123]
	v_mfma_f32_16x16x32_bf16 v[112:115], v[172:175], v[218:221], v[112:115]
	v_mfma_f32_16x16x32_bf16 v[104:107], v[164:167], v[226:229], v[104:107]
	v_mfma_f32_16x16x32_bf16 v[96:99], v[172:175], v[226:229], v[96:99]
	v_mfma_f32_16x16x32_bf16 v[88:91], v[164:167], v[234:237], v[88:91]
	v_mfma_f32_16x16x32_bf16 v[80:83], v[172:175], v[234:237], v[80:83]
	s_setprio 0
	s_setprio 1
	v_mfma_f32_16x16x32_bf16 v[116:119], v[176:179], v[192:195], 0
	v_mfma_f32_16x16x32_bf16 v[108:111], v[184:187], v[192:195], 0
	v_mfma_f32_16x16x32_bf16 v[100:103], v[176:179], v[214:217], 0
	v_mfma_f32_16x16x32_bf16 v[92:95], v[184:187], v[214:217], 0
	v_mfma_f32_16x16x32_bf16 v[84:87], v[176:179], v[222:225], 0
	v_mfma_f32_16x16x32_bf16 v[76:79], v[184:187], v[222:225], 0
	v_mfma_f32_16x16x32_bf16 v[72:75], v[176:179], v[230:233], 0
	v_mfma_f32_16x16x32_bf16 v[68:71], v[184:187], v[230:233], 0
	v_mfma_f32_16x16x32_bf16 v[116:119], v[180:183], v[196:199], v[116:119]
	v_mfma_f32_16x16x32_bf16 v[108:111], v[188:191], v[196:199], v[108:111]
	v_mfma_f32_16x16x32_bf16 v[100:103], v[180:183], v[218:221], v[100:103]
	v_mfma_f32_16x16x32_bf16 v[92:95], v[188:191], v[218:221], v[92:95]
	v_mfma_f32_16x16x32_bf16 v[84:87], v[180:183], v[226:229], v[84:87]
	v_mfma_f32_16x16x32_bf16 v[76:79], v[188:191], v[226:229], v[76:79]
	v_mfma_f32_16x16x32_bf16 v[72:75], v[180:183], v[234:237], v[72:75]
	v_mfma_f32_16x16x32_bf16 v[68:71], v[188:191], v[234:237], v[68:71]
	s_setprio 0
	s_barrier
	s_add_i32 s43, s43, s95
	v_lshl_add_u64 v[132:133], s[24:25], 0, v[148:149]
	s_mov_b32 m0, s43
	ds_read_b128 v[192:195], v163 offset:16384
	ds_read_b128 v[196:199], v163 offset:17408
	ds_read_b128 v[214:217], v163 offset:18432
	ds_read_b128 v[218:221], v163 offset:19456
	ds_read_b128 v[222:225], v163 offset:20480
	ds_read_b128 v[226:229], v163 offset:21504
	ds_read_b128 v[230:233], v163 offset:22528
	ds_read_b128 v[234:237], v163 offset:23552
	global_load_lds_dwordx4 v[132:133], off
	s_add_i32 m0, s43, 0x2000
	s_add_u32 s86, s24, 0x40000
	v_lshl_add_u64 v[134:135], s[24:25], 0, v[0:1]
	s_addc_u32 s87, s25, 0
	s_add_i32 s43, s68, s95
	global_load_lds_dwordx4 v[134:135], off
	v_lshl_add_u64 v[140:141], s[86:87], 0, v[148:149]
	s_mov_b32 m0, s43
	v_lshl_add_u64 v[142:143], s[26:27], 0, v[146:147]
	global_load_lds_dwordx4 v[140:141], off
	v_lshl_add_u64 v[140:141], s[86:87], 0, v[0:1]
	s_add_i32 m0, s43, 0x2000
	s_nop 0
	global_load_lds_dwordx4 v[140:141], off
	v_lshl_add_u64 v[140:141], s[26:27], 0, v[150:151]
	s_mov_b32 m0, s97
	s_nop 0
	global_load_lds_dwordx4 v[140:141], off
	s_mov_b32 m0, s22
	s_nop 0
	global_load_lds_dwordx4 v[142:143], off
	s_waitcnt vmcnt(8)
	s_waitcnt lgkmcnt(0)
	s_barrier
; #define PG8_STAGE(bufoff, gbase, voff) do { _Pragma("unroll") for (int _i = 0; _i < 2; ++_i) \
;         __builtin_amdgcn_global_load_lds((const unsigned*)((const char*)(gbase) + (voff)[_i]), (LAS unsigned*)(lds + (bufoff) + ldsw + _i * 8192), 16, 0, 0); } while (0)
; #define PG8_LDA(dst, b, h) do { _Pragma("unroll") for (int m = 0; m < 4; ++m) _Pragma("unroll") for (int k = 0; k < 2; ++k) dst[m][k] = *(const LAS bf16x8*)(lds + PG8_SA(b, h) + aoff + m * 2048 + k * 1024); } while (0)
; #define PG8_LDB(dst, b, h) do { _Pragma("unroll") for (int n = 0; n < 2; ++n) _Pragma("unroll") for (int k = 0; k < 2; ++k) dst[n][k] = *(const LAS bf16x8*)(lds + PG8_SB(b, h) + boff + n * 2048 + k * 1024); } while (0)
; #define PG8_MMA(ai, bj, At, Bt) do { __builtin_amdgcn_s_setprio(1); _Pragma("unroll") for (int m = 0; m < 4; ++m) _Pragma("unroll") for (int n = 0; n < 2; ++n) _Pragma("unroll") for (int k = 0; k < 2; ++k) \
;         acc[ai][bj][m][n] = __builtin_amdgcn_mfma_f32_16x16x32_bf16(Bt[n][k], At[m][k], acc[ai][bj][m][n], 0, 0, 0); __builtin_amdgcn_s_setprio(0); } while (0)
; #define PG8_WAIT_V(n) asm volatile("s_waitcnt vmcnt(" #n ")" ::: "memory")
; #define PG8_WAIT_L(n) asm volatile("s_waitcnt lgkmcnt(" #n ")" ::: "memory")
; #define PG8_BAR __builtin_amdgcn_s_barrier()
; #define PG8_SCHED __builtin_amdgcn_sched_barrier(0)
; template <class Epi>
; __device__ __forceinline__ void gemm_phase(LAS unsigned char* lds, const Gemm g, const int G, const int cidx, const Epi& E) {
;     ...
;             PG8_LDA(At, 0, 1); PG8_STAGE(PG8_SB(0, 0), b2, voffB); PG8_STAGE(PG8_SB(0, 1), b2 + hstep, voffB); PG8_STAGE(PG8_SA(0, 0), a2, voffA);
;             PG8_WAIT_V(8); PG8_WAIT_L(0); PG8_BAR; PG8_MMA(1, 0, At, B0); PG8_MMA(1, 1, At, B1); PG8_BAR; PG8_SCHED;
;             PG8_LDB(B0, 1, 0); PG8_LDB(B1, 1, 1); PG8_SCHED; PG8_LDA(At, 1, 0); PG8_STAGE(PG8_SA(0, 1), a2 + hstep, voffA);
;             PG8_WAIT_V(8); PG8_WAIT_L(0); PG8_BAR; PG8_MMA(0, 0, At, B0); PG8_MMA(0, 1, At, B1); PG8_BAR; PG8_SCHED;
	s_setprio 1
	s_waitcnt lgkmcnt(0)
	v_mfma_f32_16x16x32_bf16 v[64:67], v[158:161], v[192:195], 0
	v_mfma_f32_16x16x32_bf16 v[60:63], v[168:171], v[192:195], 0
	v_mfma_f32_16x16x32_bf16 v[56:59], v[158:161], v[214:217], 0
	v_mfma_f32_16x16x32_bf16 v[48:51], v[168:171], v[214:217], 0
	v_mfma_f32_16x16x32_bf16 v[40:43], v[158:161], v[222:225], 0
	v_mfma_f32_16x16x32_bf16 v[32:35], v[168:171], v[222:225], 0
	v_mfma_f32_16x16x32_bf16 v[24:27], v[158:161], v[230:233], 0
	v_mfma_f32_16x16x32_bf16 v[16:19], v[168:171], v[230:233], 0
	v_mfma_f32_16x16x32_bf16 v[64:67], v[164:167], v[196:199], v[64:67]
	v_mfma_f32_16x16x32_bf16 v[60:63], v[172:175], v[196:199], v[60:63]
	v_mfma_f32_16x16x32_bf16 v[56:59], v[164:167], v[218:221], v[56:59]
	v_mfma_f32_16x16x32_bf16 v[48:51], v[172:175], v[218:221], v[48:51]
	v_mfma_f32_16x16x32_bf16 v[40:43], v[164:167], v[226:229], v[40:43]
	v_mfma_f32_16x16x32_bf16 v[32:35], v[172:175], v[226:229], v[32:35]
	v_mfma_f32_16x16x32_bf16 v[24:27], v[164:167], v[234:237], v[24:27]
	v_mfma_f32_16x16x32_bf16 v[16:19], v[172:175], v[234:237], v[16:19]
	s_setprio 0
	s_setprio 1
	v_mfma_f32_16x16x32_bf16 v[52:55], v[176:179], v[192:195], 0
	v_mfma_f32_16x16x32_bf16 v[44:47], v[184:187], v[192:195], 0
	v_mfma_f32_16x16x32_bf16 v[36:39], v[176:179], v[214:217], 0
	v_mfma_f32_16x16x32_bf16 v[28:31], v[184:187], v[214:217], 0
	v_mfma_f32_16x16x32_bf16 v[20:23], v[176:179], v[222:225], 0
	v_mfma_f32_16x16x32_bf16 v[12:15], v[184:187], v[222:225], 0
	v_mfma_f32_16x16x32_bf16 v[8:11], v[176:179], v[230:233], 0
	v_mfma_f32_16x16x32_bf16 v[4:7], v[184:187], v[230:233], 0
	v_mfma_f32_16x16x32_bf16 v[52:55], v[180:183], v[196:199], v[52:55]
	v_mfma_f32_16x16x32_bf16 v[44:47], v[188:191], v[196:199], v[44:47]
	v_mfma_f32_16x16x32_bf16 v[36:39], v[180:183], v[218:221], v[36:39]
	v_mfma_f32_16x16x32_bf16 v[28:31], v[188:191], v[218:221], v[28:31]
	v_mfma_f32_16x16x32_bf16 v[20:23], v[180:183], v[226:229], v[20:23]
	v_mfma_f32_16x16x32_bf16 v[12:15], v[188:191], v[226:229], v[12:15]
	v_mfma_f32_16x16x32_bf16 v[8:11], v[180:183], v[234:237], v[8:11]
	v_mfma_f32_16x16x32_bf16 v[4:7], v[188:191], v[234:237], v[4:7]
	s_setprio 0
	s_barrier
	s_add_i32 s43, 0, 0x18000
	s_add_i32 s68, 0, 0x1c000
	v_add_u32_e32 v172, s43, v145
	v_add_u32_e32 v188, s68, v145
	ds_read_b128 v[158:161], v172
	ds_read_b128 v[164:167], v172 offset:1024
	ds_read_b128 v[168:171], v172 offset:2048
	ds_read_b128 v[172:175], v172 offset:3072
	ds_read_b128 v[176:179], v188
	ds_read_b128 v[180:183], v188 offset:1024
	ds_read_b128 v[184:187], v188 offset:2048
	ds_read_b128 v[188:191], v188 offset:3072
	s_add_u32 s26, s26, 0x40000
	s_addc_u32 s27, s27, 0
	s_mov_b32 m0, s16
	v_lshl_add_u64 v[200:201], s[26:27], 0, v[150:151]
	ds_read_b128 v[192:195], v163 offset:32768
	ds_read_b128 v[196:199], v163 offset:33792
	ds_read_b128 v[214:217], v163 offset:34816
	ds_read_b128 v[218:221], v163 offset:35840
	ds_read_b128 v[222:225], v163 offset:36864
	ds_read_b128 v[226:229], v163 offset:37888
	ds_read_b128 v[230:233], v163 offset:38912
	ds_read_b128 v[234:237], v163 offset:39936
	global_load_lds_dwordx4 v[200:201], off
	v_lshl_add_u64 v[200:201], s[26:27], 0, v[146:147]
	s_mov_b32 m0, s17
	s_nop 0
	global_load_lds_dwordx4 v[200:201], off
	s_waitcnt vmcnt(8)
	s_waitcnt lgkmcnt(0)
	s_barrier
	s_setprio 1
	s_waitcnt lgkmcnt(0)
	v_mfma_f32_16x16x32_bf16 v[128:131], v[158:161], v[192:195], v[128:131]
	v_mfma_f32_16x16x32_bf16 v[124:127], v[168:171], v[192:195], v[124:127]
	v_mfma_f32_16x16x32_bf16 v[120:123], v[158:161], v[214:217], v[120:123]
	v_mfma_f32_16x16x32_bf16 v[112:115], v[168:171], v[214:217], v[112:115]
	v_mfma_f32_16x16x32_bf16 v[104:107], v[158:161], v[222:225], v[104:107]
	v_mfma_f32_16x16x32_bf16 v[96:99], v[168:171], v[222:225], v[96:99]
	v_mfma_f32_16x16x32_bf16 v[88:91], v[158:161], v[230:233], v[88:91]
	v_mfma_f32_16x16x32_bf16 v[80:83], v[168:171], v[230:233], v[80:83]
	v_mfma_f32_16x16x32_bf16 v[128:131], v[164:167], v[196:199], v[128:131]
	v_mfma_f32_16x16x32_bf16 v[124:127], v[172:175], v[196:199], v[124:127]
	v_mfma_f32_16x16x32_bf16 v[120:123], v[164:167], v[218:221], v[120:123]
	v_mfma_f32_16x16x32_bf16 v[112:115], v[172:175], v[218:221], v[112:115]
	v_mfma_f32_16x16x32_bf16 v[104:107], v[164:167], v[226:229], v[104:107]
	v_mfma_f32_16x16x32_bf16 v[96:99], v[172:175], v[226:229], v[96:99]
	v_mfma_f32_16x16x32_bf16 v[88:91], v[164:167], v[234:237], v[88:91]
	v_mfma_f32_16x16x32_bf16 v[80:83], v[172:175], v[234:237], v[80:83]
	s_setprio 0
	s_setprio 1
	v_mfma_f32_16x16x32_bf16 v[116:119], v[176:179], v[192:195], v[116:119]
	v_mfma_f32_16x16x32_bf16 v[108:111], v[184:187], v[192:195], v[108:111]
	v_mfma_f32_16x16x32_bf16 v[100:103], v[176:179], v[214:217], v[100:103]
	v_mfma_f32_16x16x32_bf16 v[92:95], v[184:187], v[214:217], v[92:95]
	v_mfma_f32_16x16x32_bf16 v[84:87], v[176:179], v[222:225], v[84:87]
	v_mfma_f32_16x16x32_bf16 v[76:79], v[184:187], v[222:225], v[76:79]
	v_mfma_f32_16x16x32_bf16 v[72:75], v[176:179], v[230:233], v[72:75]
	v_mfma_f32_16x16x32_bf16 v[68:71], v[184:187], v[230:233], v[68:71]
	v_mfma_f32_16x16x32_bf16 v[116:119], v[180:183], v[196:199], v[116:119]
	v_mfma_f32_16x16x32_bf16 v[108:111], v[188:191], v[196:199], v[108:111]
	v_mfma_f32_16x16x32_bf16 v[100:103], v[180:183], v[218:221], v[100:103]
	v_mfma_f32_16x16x32_bf16 v[92:95], v[188:191], v[218:221], v[92:95]
	v_mfma_f32_16x16x32_bf16 v[84:87], v[180:183], v[226:229], v[84:87]
	v_mfma_f32_16x16x32_bf16 v[76:79], v[188:191], v[226:229], v[76:79]
	v_mfma_f32_16x16x32_bf16 v[72:75], v[180:183], v[234:237], v[72:75]
	v_mfma_f32_16x16x32_bf16 v[68:71], v[188:191], v[234:237], v[68:71]
	s_setprio 0
	s_barrier
; #define PG8_STAGE(bufoff, gbase, voff) do { _Pragma("unroll") for (int _i = 0; _i < 2; ++_i) \
;         __builtin_amdgcn_global_load_lds((const unsigned*)((const char*)(gbase) + (voff)[_i]), (LAS unsigned*)(lds + (bufoff) + ldsw + _i * 8192), 16, 0, 0); } while (0)
; #define PG8_LDA(dst, b, h) do { _Pragma("unroll") for (int m = 0; m < 4; ++m) _Pragma("unroll") for (int k = 0; k < 2; ++k) dst[m][k] = *(const LAS bf16x8*)(lds + PG8_SA(b, h) + aoff + m * 2048 + k * 1024); } while (0)
; #define PG8_MMA(ai, bj, At, Bt) do { __builtin_amdgcn_s_setprio(1); _Pragma("unroll") for (int m = 0; m < 4; ++m) _Pragma("unroll") for (int n = 0; n < 2; ++n) _Pragma("unroll") for (int k = 0; k < 2; ++k) \
;         acc[ai][bj][m][n] = __builtin_amdgcn_mfma_f32_16x16x32_bf16(Bt[n][k], At[m][k], acc[ai][bj][m][n], 0, 0, 0); __builtin_amdgcn_s_setprio(0); } while (0)
; #define PG8_WAIT_V(n) asm volatile("s_waitcnt vmcnt(" #n ")" ::: "memory")
; #define PG8_WAIT_L(n) asm volatile("s_waitcnt lgkmcnt(" #n ")" ::: "memory")
; #define PG8_BAR __builtin_amdgcn_s_barrier()
; #define PG8_SCHED __builtin_amdgcn_sched_barrier(0)
; template <class Epi>
; __device__ __forceinline__ void gemm_phase(LAS unsigned char* lds, const Gemm g, const int G, const int cidx, const Epi& E) {
;     ...
;             PG8_LDA(At, 1, 1); PG8_STAGE(PG8_SB(1, 0), b3, voffB); PG8_STAGE(PG8_SB(1, 1), b3 + hstep, voffB); PG8_STAGE(PG8_SA(1, 0), a3, voffA);
;             PG8_WAIT_V(8); PG8_WAIT_L(0); PG8_BAR; PG8_MMA(1, 0, At, B0); PG8_MMA(1, 1, At, B1); PG8_BAR; PG8_SCHED;
	s_add_i32 s26, s43, s95
	v_lshl_add_u64 v[132:133], v[132:133], 0, s[46:47]
	s_mov_b32 m0, s26
	ds_read_b128 v[192:195], v163 offset:49152
	ds_read_b128 v[196:199], v163 offset:50176
	ds_read_b128 v[214:217], v163 offset:51200
	ds_read_b128 v[218:221], v163 offset:52224
	ds_read_b128 v[222:225], v163 offset:53248
	ds_read_b128 v[226:229], v163 offset:54272
	ds_read_b128 v[230:233], v163 offset:55296
	ds_read_b128 v[234:237], v163 offset:56320
	global_load_lds_dwordx4 v[132:133], off
	s_add_i32 m0, s26, 0x2000
	s_add_u32 s24, s24, 0x40080
	v_lshl_add_u64 v[132:133], v[134:135], 0, s[46:47]
	s_addc_u32 s25, s25, 0
	s_add_i32 s26, s68, s95
	global_load_lds_dwordx4 v[132:133], off
	v_lshl_add_u64 v[132:133], s[24:25], 0, v[148:149]
	s_mov_b32 m0, s26
	s_nop 0
	global_load_lds_dwordx4 v[132:133], off
	v_lshl_add_u64 v[132:133], s[24:25], 0, v[0:1]
	s_add_i32 m0, s26, 0x2000
	s_nop 0
	global_load_lds_dwordx4 v[132:133], off
	v_lshl_add_u64 v[132:133], v[140:141], 0, s[46:47]
	s_mov_b32 m0, s84
	s_nop 0
	global_load_lds_dwordx4 v[132:133], off
	v_lshl_add_u64 v[132:133], v[142:143], 0, s[46:47]
	s_mov_b32 m0, s76
	s_nop 0
	global_load_lds_dwordx4 v[132:133], off
	s_waitcnt vmcnt(8)
	s_waitcnt lgkmcnt(0)
	s_barrier
	s_setprio 1
	s_waitcnt lgkmcnt(0)
	v_mfma_f32_16x16x32_bf16 v[64:67], v[158:161], v[192:195], v[64:67]
	v_mfma_f32_16x16x32_bf16 v[60:63], v[168:171], v[192:195], v[60:63]
	v_mfma_f32_16x16x32_bf16 v[56:59], v[158:161], v[214:217], v[56:59]
	v_mfma_f32_16x16x32_bf16 v[48:51], v[168:171], v[214:217], v[48:51]
	v_mfma_f32_16x16x32_bf16 v[40:43], v[158:161], v[222:225], v[40:43]
	v_mfma_f32_16x16x32_bf16 v[32:35], v[168:171], v[222:225], v[32:35]
	v_mfma_f32_16x16x32_bf16 v[24:27], v[158:161], v[230:233], v[24:27]
	v_mfma_f32_16x16x32_bf16 v[16:19], v[168:171], v[230:233], v[16:19]
	v_mfma_f32_16x16x32_bf16 v[64:67], v[164:167], v[196:199], v[64:67]
	v_mfma_f32_16x16x32_bf16 v[60:63], v[172:175], v[196:199], v[60:63]
	v_mfma_f32_16x16x32_bf16 v[56:59], v[164:167], v[218:221], v[56:59]
	v_mfma_f32_16x16x32_bf16 v[48:51], v[172:175], v[218:221], v[48:51]
	v_mfma_f32_16x16x32_bf16 v[40:43], v[164:167], v[226:229], v[40:43]
	v_mfma_f32_16x16x32_bf16 v[32:35], v[172:175], v[226:229], v[32:35]
	v_mfma_f32_16x16x32_bf16 v[24:27], v[164:167], v[234:237], v[24:27]
	v_mfma_f32_16x16x32_bf16 v[16:19], v[172:175], v[234:237], v[16:19]
	s_setprio 0
	s_setprio 1
	v_mfma_f32_16x16x32_bf16 v[52:55], v[176:179], v[192:195], v[52:55]
	v_mfma_f32_16x16x32_bf16 v[44:47], v[184:187], v[192:195], v[44:47]
	v_mfma_f32_16x16x32_bf16 v[36:39], v[176:179], v[214:217], v[36:39]
	v_mfma_f32_16x16x32_bf16 v[28:31], v[184:187], v[214:217], v[28:31]
	v_mfma_f32_16x16x32_bf16 v[20:23], v[176:179], v[222:225], v[20:23]
	v_mfma_f32_16x16x32_bf16 v[12:15], v[184:187], v[222:225], v[12:15]
	v_mfma_f32_16x16x32_bf16 v[8:11], v[176:179], v[230:233], v[8:11]
	v_mfma_f32_16x16x32_bf16 v[4:7], v[184:187], v[230:233], v[4:7]
	v_mfma_f32_16x16x32_bf16 v[52:55], v[180:183], v[196:199], v[52:55]
	v_mfma_f32_16x16x32_bf16 v[44:47], v[188:191], v[196:199], v[44:47]
	v_mfma_f32_16x16x32_bf16 v[36:39], v[180:183], v[218:221], v[36:39]
	v_mfma_f32_16x16x32_bf16 v[28:31], v[188:191], v[218:221], v[28:31]
	v_mfma_f32_16x16x32_bf16 v[20:23], v[180:183], v[226:229], v[20:23]
	v_mfma_f32_16x16x32_bf16 v[12:15], v[188:191], v[226:229], v[12:15]
	v_mfma_f32_16x16x32_bf16 v[8:11], v[180:183], v[234:237], v[8:11]
	v_mfma_f32_16x16x32_bf16 v[4:7], v[188:191], v[234:237], v[4:7]
	s_setprio 0
	s_barrier
	s_add_i32 s45, s45, 2
	s_add_u32 s42, s42, 0x100
	s_addc_u32 s44, s44, 0
	s_add_u32 s20, s20, 0x100
	s_addc_u32 s21, s21, 0
